# mixer_out: the 32 per-lane gate values are read from LDS in one batch right behind the barrier (were 32 serialized read-compute-write round trips)
# baseline (speedup 1.0000x reference)
; #define LAS __attribute__((address_space(3)))
; __device__ __forceinline__ void mixer_out_phase(const Ctx& X, LAS unsigned char* lds, int layer, int tid, int wave, int lane) {
;     ...
;     for (int u = blockIdx.x; u < 1536; u += gridDim.x) {
;         asm volatile("" : "+v"(lane), "+v"(tid));
;         LAS bf16_t* GT = opq((LAS bf16_t*)lds);
;         const int r = lane & 15, q = lane >> 4, h = wave >> 1, half = wave & 1;
;         const int mixer = u >> 9, rem = u & 511, b = rem >> 7, c = rem & 127;
;         const int uid = unit_id(mixer, b, h, c);
;         const int goff = mixer == 0 ? C_RG : (mixer == 1 ? C_GG : C_HG), moff = mixer == 0 ? 0 : (mixer == 1 ? 512 : 768);
;         const size_t row0 = (size_t)b * T + c * 64;
;         u32x4 gv[4];
; #pragma unroll
;         for (int n = 0; n < 4; ++n) { const int idx = tid + 512 * n; gv[n] = *(const u32x4*)(proj + (row0 + (idx >> 5)) * LDP + goff + (idx & 31) * 8); }
;         const bf16_t* qe = WSP(const bf16_t, WS_QEFF) + (size_t)uid * 4096;
;         const bf16_t* st = WSP(const bf16_t, WS_BCS) + (size_t)uid * 4096;
;         bf16x8 a[2][2], bb[4][2]; u32x4 ov[2][2];
; #pragma unroll
;         for (int rt = 0; rt < 2; ++rt) { const int rt4 = 2 * half + rt;
; #pragma unroll
;             for (int ks = 0; ks < 2; ++ks) a[rt][ks] = *(const bf16x8*)(qe + (16 * rt4 + r) * 64 + ks * 32 + q * 8);
;             const u32x4* ol = (const u32x4*)(WSP(const bf16_t, WS_OLOC) + ((size_t)uid * 4 + rt4) * 1024 + lane * 16); ov[rt][0] = ol[0]; ov[rt][1] = ol[1]; }
; #pragma unroll
;         for (int ct = 0; ct < 4; ++ct)
; #pragma unroll
;             for (int ks = 0; ks < 2; ++ks) { const bf16_t* tb = st + (size_t)((ct * 4 + 2 * ks + (q >> 1)) * 64) * 4;
;                 const u32x2 lo = *(const u32x2*)(tb + ((2 * (q & 1)) * 16 + r) * 4), hi = *(const u32x2*)(tb + ((2 * (q & 1) + 1) * 16 + r) * 4);
;                 bb[ct][ks] = __builtin_bit_cast(bf16x8, (u32x4){lo.x, lo.y, hi.x, hi.y}); }
;         const float* nw = mixer == 0 ? X.in[3] + layer * 256 + h * 64 : (mixer == 1 ? X.in[11] + layer * 64 : X.in[13] + layer * 64);
;         float wv[4];
; #pragma unroll
;         for (int ct = 0; ct < 4; ++ct) wv[ct] = nw[16 * ct + r];
; #pragma unroll
;         for (int n = 0; n < 4; ++n) { const int idx = tid + 512 * n; *(LAS u32x4*)(GT + (idx >> 5) * GP + (idx & 31) * 8) = gv[n]; }
;         LBAR();
.LBB0_888:
	s_ashr_i32 s6, s10, 9
	s_cmp_eq_u32 s6, 1
	s_movk_i32 s0, 0xd00
	s_cselect_b32 s7, 0x900, s0
	s_movk_i32 s0, 0x200
	s_cselect_b32 s11, s0, 0x300
	s_cselect_b32 s12, s50, s54
	s_cselect_b32 s13, s51, s55
	s_cmpk_lt_u32 s10, 0x200
	s_cselect_b64 s[0:1], -1, 0
	s_and_b64 s[0:1], s[0:1], exec
	s_cselect_b32 s11, 0, s11
	s_add_u32 s12, s12, s4
	s_addc_u32 s13, s13, s5
	s_cmpk_lt_u32 s10, 0x200
	s_cselect_b64 vcc, -1, 0
	s_and_b64 s[0:1], vcc, exec
	s_cselect_b32 s7, 0x300, s7
	s_cselect_b32 s1, s9, s13
	s_cselect_b32 s0, s8, s12
	s_bfe_u32 s12, s10, 0x20007
	s_and_b32 s13, s10, 0x7f
	s_lshl_b32 s14, s12, 9
	s_lshl_b32 s15, s6, 11
	s_lshl_b32 s6, s12, 13
	s_lshl_b32 s12, s13, 6
	s_or_b32 s16, s6, s12
	s_lshl_b32 s6, s7, 1
	s_add_u32 s6, s76, s6
	s_waitcnt vmcnt(0)
	v_lshlrev_b32_e32 v6, 4, v104
	v_ashrrev_i32_e32 v94, 5, v104
	s_addc_u32 s7, s77, 0
	v_and_b32_e32 v156, 0x1f0, v6
	v_ashrrev_i32_e32 v95, 31, v94
	v_lshl_add_u64 v[6:7], s[6:7], 0, v[156:157]
	v_lshl_add_u64 v[92:93], s[16:17], 0, v[94:95]
	v_mov_b32_e32 v108, v157
	v_mad_i64_i32 v[8:9], s[6:7], v92, s71, v[6:7]
	global_load_dwordx4 v[62:65], v[8:9], off
	v_add_u32_e32 v8, 0x200, v104
	v_ashrrev_i32_e32 v98, 5, v8
	v_ashrrev_i32_e32 v99, 31, v98
	v_lshl_add_u64 v[90:91], s[16:17], 0, v[98:99]
	v_mad_i64_i32 v[8:9], s[6:7], v90, s71, v[6:7]
	global_load_dwordx4 v[74:77], v[8:9], off
	v_add_u32_e32 v8, 0x400, v104
	v_ashrrev_i32_e32 v100, 5, v8
	v_ashrrev_i32_e32 v101, 31, v100
	v_lshl_add_u64 v[88:89], s[16:17], 0, v[100:101]
	v_mad_i64_i32 v[8:9], s[6:7], v88, s71, v[6:7]
	global_load_dwordx4 v[78:81], v[8:9], off
	v_add_u32_e32 v8, 0x600, v104
	v_ashrrev_i32_e32 v102, 5, v8
	v_ashrrev_i32_e32 v103, 31, v102
	v_lshl_add_u64 v[86:87], s[16:17], 0, v[102:103]
	v_mad_i64_i32 v[6:7], s[6:7], v86, s71, v[6:7]
	s_or_b32 s6, s13, s23
	s_add_i32 s6, s6, s15
	s_add_i32 s6, s6, s14
	s_ashr_i32 s7, s6, 31
	s_waitcnt vmcnt(14)
	v_ashrrev_i32_e32 v110, 4, v105
	s_lshl_b64 s[6:7], s[6:7], 13
	global_load_dwordx4 v[82:85], v[6:7], off
	s_add_u32 s12, s89, s6
	v_lshlrev_b32_e32 v6, 3, v110
	s_addc_u32 s13, s78, s7
	v_ashrrev_i32_e32 v7, 31, v6
	v_and_b32_e32 v109, 15, v105
	v_lshl_add_u64 v[6:7], v[6:7], 1, s[12:13]
	s_add_u32 s12, s19, s6
	s_addc_u32 s13, s20, s7
	s_lshl_b32 s16, s21, 1
	v_lshlrev_b32_e32 v22, 7, v110
	v_lshlrev_b32_e32 v95, 2, v109
	s_add_u32 s6, s74, s6
	v_and_or_b32 v22, v22, s33, v95
	s_addc_u32 s7, s75, s7
	v_lshlrev_b32_e32 v22, 1, v22
	v_mov_b32_e32 v23, v157
	v_lshlrev_b32_e32 v12, 6, v109
	v_lshlrev_b32_e32 v8, 4, v105
	v_lshl_add_u64 v[50:51], s[6:7], 0, v[22:23]
	v_lshlrev_b32_e32 v22, 1, v105
	v_ashrrev_i32_e32 v9, 31, v8
	v_or_b32_e32 v10, s21, v12
	v_and_b32_e32 v52, 0xffffffc0, v22
	v_lshl_add_u64 v[8:9], v[8:9], 1, s[12:13]
	v_lshlrev_b32_e32 v10, 1, v10
	v_mov_b32_e32 v11, v157
	v_add_u32_e32 v26, 0x80, v52
	v_add_u32_e32 v30, 0x100, v52
	v_lshl_add_u64 v[10:11], v[6:7], 0, v[10:11]
	v_lshl_add_u64 v[18:19], v[8:9], 0, s[16:17]
	v_add_lshl_u32 v8, v12, s21, 1
	v_mov_b32_e32 v9, v157
	v_ashrrev_i32_e32 v53, 31, v52
	v_ashrrev_i32_e32 v27, 31, v26
	v_ashrrev_i32_e32 v31, 31, v30
	global_load_dwordx4 v[66:69], v[10:11], off
	global_load_dwordx4 v[70:73], v[10:11], off offset:64
	global_load_dwordx4 v[54:57], v[18:19], off offset:16
	global_load_dwordx4 v[58:61], v[18:19], off
	v_lshl_add_u64 v[10:11], v[6:7], 0, v[8:9]
	s_waitcnt vmcnt(12)
	v_lshl_add_u64 v[24:25], v[52:53], 3, v[50:51]
	v_lshl_add_u64 v[28:29], v[26:27], 3, v[50:51]
	v_lshl_add_u64 v[32:33], v[30:31], 3, v[50:51]
	global_load_dwordx4 v[6:9], v[10:11], off offset:2048
	s_nop 0
	global_load_dwordx4 v[10:13], v[10:11], off offset:2112
	s_nop 0
	global_load_dwordx4 v[14:17], v[18:19], off offset:2064
	s_nop 0
	global_load_dwordx4 v[18:21], v[18:19], off offset:2048
	s_nop 0
	global_load_dwordx2 v[22:23], v[24:25], off
	s_nop 0
	global_load_dwordx2 v[24:25], v[24:25], off offset:128
	s_nop 0
	global_load_dwordx2 v[26:27], v[28:29], off
	s_nop 0
	global_load_dwordx2 v[28:29], v[28:29], off offset:128
	s_nop 0
	global_load_dwordx2 v[30:31], v[32:33], off
	s_nop 0
	global_load_dwordx2 v[32:33], v[32:33], off offset:128
	v_add_u32_e32 v34, 0x180, v52
	v_add_u32_e32 v38, 0x200, v52
	v_add_u32_e32 v42, 0x280, v52
	v_add_u32_e32 v46, 0x300, v52
	v_ashrrev_i32_e32 v35, 31, v34
	v_ashrrev_i32_e32 v39, 31, v38
	v_ashrrev_i32_e32 v43, 31, v42
	v_ashrrev_i32_e32 v47, 31, v46
	v_lshl_add_u64 v[36:37], v[34:35], 3, v[50:51]
	v_lshl_add_u64 v[40:41], v[38:39], 3, v[50:51]
	v_lshl_add_u64 v[44:45], v[42:43], 3, v[50:51]
	v_lshl_add_u64 v[48:49], v[46:47], 3, v[50:51]
	global_load_dwordx2 v[34:35], v[36:37], off
	s_nop 0
	global_load_dwordx2 v[36:37], v[36:37], off offset:128
	s_nop 0
	global_load_dwordx2 v[38:39], v[40:41], off
	s_nop 0
	global_load_dwordx2 v[40:41], v[40:41], off offset:128
	s_nop 0
	global_load_dwordx2 v[42:43], v[44:45], off
	s_nop 0
	global_load_dwordx2 v[44:45], v[44:45], off offset:128
	s_nop 0
	global_load_dwordx2 v[46:47], v[48:49], off
	s_nop 0
	global_load_dwordx2 v[48:49], v[48:49], off offset:128
	v_add_u32_e32 v52, 0x380, v52
	v_ashrrev_i32_e32 v53, 31, v52
	v_lshl_add_u64 v[52:53], v[52:53], 3, v[50:51]
	global_load_dwordx2 v[50:51], v[52:53], off
	s_nop 0
	global_load_dwordx2 v[52:53], v[52:53], off offset:128
	v_add_u32_e32 v112, v108, v156
	global_load_dword v106, v95, s[0:1]
	global_load_dword v103, v95, s[0:1] offset:64
	global_load_dword v101, v95, s[0:1] offset:128
	global_load_dword v99, v95, s[0:1] offset:192
	v_mad_u64_u32 v[96:97], s[0:1], v94, s34, v[112:113]
	s_waitcnt vmcnt(31)
	ds_write_b128 v96, v[62:65]
	v_mad_u64_u32 v[94:95], s[0:1], v98, s34, v[112:113]
	v_and_b32_e32 v63, 64, v230
	s_waitcnt vmcnt(30)
	ds_write_b128 v94, v[74:77]
	v_mad_u64_u32 v[76:77], s[0:1], v100, s34, v[112:113]
	v_mad_u64_u32 v[74:75], s[0:1], v102, s34, v[112:113]
	v_xor_b32_e32 v62, 1, v230
	v_add_u32_e32 v63, 64, v63
	v_cmp_lt_i32_e64 s[0:1], v62, v63
	s_waitcnt vmcnt(29)
	ds_write_b128 v76, v[78:81]
	s_waitcnt vmcnt(28)
	ds_write_b128 v74, v[82:85]
	v_cndmask_b32_e64 v62, v230, v62, s[0:1]
	v_lshlrev_b32_e32 v75, 2, v62
	v_xor_b32_e32 v62, 2, v230
	v_cmp_lt_i32_e64 s[0:1], v62, v63
	v_lshl_add_u32 v84, v110, 2, s22
	v_add_u32_e32 v85, s23, v108
	v_cndmask_b32_e64 v62, v230, v62, s[0:1]
	v_lshlrev_b32_e32 v77, 2, v62
	v_xor_b32_e32 v62, 4, v230
	v_cmp_lt_i32_e64 s[0:1], v62, v63
	v_lshlrev_b32_e32 v95, 1, v109
	v_cndmask_b32_e32 v107, v225, v229, vcc
	v_cndmask_b32_e64 v62, v230, v62, s[0:1]
	v_lshlrev_b32_e32 v78, 2, v62
	v_xor_b32_e32 v62, 8, v230
	v_cmp_lt_i32_e64 s[0:1], v62, v63
	s_waitcnt lgkmcnt(0)
	s_barrier
; #define LAS __attribute__((address_space(3)))
; __device__ __forceinline__ float bf_lo(unsigned u) { return __uint_as_float(u << 16); }
; __device__ __forceinline__ float bf_hi(unsigned u) { return __uint_as_float(u & 0xffff0000u); }
; __device__ __forceinline__ float bf2f(bf16_t b) { return __uint_as_float((unsigned)b << 16); }
; __device__ __forceinline__ void mixer_out_phase(const Ctx& X, LAS unsigned char* lds, int layer, int tid, int wave, int lane) {
;     ...
;         LBAR();
;         const bool on = ((MIX_MASK >> (mixer == 0 ? 0 : (mixer == 1 ? 2 : 3))) & 1) != 0;
; #pragma unroll
;         for (int rt = 0; rt < 2; ++rt) {
;             f32x4 acc[4];
;             acc[0] = (f32x4){bf_lo(ov[rt][0].x), bf_hi(ov[rt][0].x), bf_lo(ov[rt][0].y), bf_hi(ov[rt][0].y)}; acc[1] = (f32x4){bf_lo(ov[rt][0].z), bf_hi(ov[rt][0].z), bf_lo(ov[rt][0].w), bf_hi(ov[rt][0].w)};
;             acc[2] = (f32x4){bf_lo(ov[rt][1].x), bf_hi(ov[rt][1].x), bf_lo(ov[rt][1].y), bf_hi(ov[rt][1].y)}; acc[3] = (f32x4){bf_lo(ov[rt][1].z), bf_hi(ov[rt][1].z), bf_lo(ov[rt][1].w), bf_hi(ov[rt][1].w)};
; #pragma unroll
;             for (int ct = 0; ct < 4; ++ct)
; #pragma unroll
;                 for (int ks = 0; ks < 2; ++ks) acc[ct] = __builtin_amdgcn_mfma_f32_16x16x32_bf16(a[rt][ks], bb[ct][ks], acc[ct], 0, 0, 0);
; #pragma unroll
;             for (int j = 0; j < 4; ++j) {
;                 float sm = (acc[0][j] + acc[1][j]) + (acc[2][j] + acc[3][j]);
;                 sm += __shfl_xor(sm, 1); sm += __shfl_xor(sm, 2); sm += __shfl_xor(sm, 4); sm += __shfl_xor(sm, 8);
;                 const float mu = mixer == 0 ? sm * (1.f / 64.f) : 0.f;
;                 float d[4], s2 = 0.f;
; #pragma unroll
;                 for (int ct = 0; ct < 4; ++ct) { d[ct] = acc[ct][j] - mu; s2 += d[ct] * d[ct]; }
;                 s2 += __shfl_xor(s2, 1); s2 += __shfl_xor(s2, 2); s2 += __shfl_xor(s2, 4); s2 += __shfl_xor(s2, 8);
;                 const float rs = rsqrtf(s2 * (1.f / 64.f) + (mixer == 0 ? 1e-5f : 1e-6f));
;                 const int ii = 16 * (2 * half + rt) + 4 * q + j;
; #pragma unroll
;                 for (int ct = 0; ct < 4; ++ct) { LAS bf16_t* gp = GT + ii * GP + h * 64 + 16 * ct + r;
;                     const float y = d[ct] * rs * wv[ct] * silu_acc(bf2f(*gp));
;                     *gp = on ? f2bf(y) : (bf16_t)0; }
	v_mul_lo_u32 v146, v84, s34
	v_add3_u32 v146, v85, v95, v146
	ds_read_u16 v134, v146
	ds_read_u16 v135, v146 offset:32
	ds_read_u16 v136, v146 offset:64
	ds_read_u16 v137, v146 offset:96
	ds_read_u16 v138, v146 offset:528
	ds_read_u16 v139, v146 offset:560
	ds_read_u16 v140, v146 offset:592
	ds_read_u16 v141, v146 offset:624
	ds_read_u16 v142, v146 offset:1056
	ds_read_u16 v143, v146 offset:1088
	ds_read_u16 v144, v146 offset:1120
	ds_read_u16 v145, v146 offset:1152
	ds_read_u16 v147, v146 offset:1584
	ds_read_u16 v148, v146 offset:1616
	ds_read_u16 v149, v146 offset:1648
	ds_read_u16 v150, v146 offset:1680
	ds_read_u16 v151, v146 offset:8448
	ds_read_u16 v152, v146 offset:8480
	ds_read_u16 v153, v146 offset:8512
	ds_read_u16 v154, v146 offset:8544
	ds_read_u16 v155, v146 offset:8976
	ds_read_u16 v182, v146 offset:9008
	ds_read_u16 v183, v146 offset:9040
	ds_read_u16 v184, v146 offset:9072
	ds_read_u16 v185, v146 offset:9504
	ds_read_u16 v186, v146 offset:9536
	ds_read_u16 v187, v146 offset:9568
	ds_read_u16 v188, v146 offset:9600
	ds_read_u16 v189, v146 offset:10032
	ds_read_u16 v190, v146 offset:10064
	ds_read_u16 v191, v146 offset:10096
	ds_read_u16 v192, v146 offset:10128
	s_waitcnt vmcnt(25)
	v_lshlrev_b32_e32 v80, 16, v54
	v_cndmask_b32_e64 v62, v230, v62, s[0:1]
	v_lshlrev_b32_e32 v79, 2, v62
	s_waitcnt vmcnt(24)
	v_lshlrev_b32_e32 v62, 16, v58
	v_and_b32_e32 v63, 0xffff0000, v58
	v_lshlrev_b32_e32 v64, 16, v59
	v_and_b32_e32 v65, 0xffff0000, v59
	v_lshlrev_b32_e32 v58, 16, v60
	v_and_b32_e32 v59, 0xffff0000, v60
	v_lshlrev_b32_e32 v60, 16, v61
	v_and_b32_e32 v61, 0xffff0000, v61
	v_and_b32_e32 v81, 0xffff0000, v54
	v_lshlrev_b32_e32 v82, 16, v55
	s_waitcnt vmcnt(14)
	v_mfma_f32_16x16x32_bf16 v[58:61], v[66:69], v[30:33], v[58:61]
	v_and_b32_e32 v83, 0xffff0000, v55
	v_lshlrev_b32_e32 v108, 16, v56
	v_and_b32_e32 v109, 0xffff0000, v56
	v_lshlrev_b32_e32 v110, 16, v57
	v_and_b32_e32 v111, 0xffff0000, v57
	v_mfma_f32_16x16x32_bf16 v[54:57], v[66:69], v[22:25], v[62:65]
	s_waitcnt vmcnt(12)
	v_mfma_f32_16x16x32_bf16 v[62:65], v[70:73], v[34:37], v[58:61]
	s_waitcnt vmcnt(10)
	v_mfma_f32_16x16x32_bf16 v[58:61], v[66:69], v[38:41], v[80:83]
	s_waitcnt vmcnt(6)
	v_mfma_f32_16x16x32_bf16 v[66:69], v[66:69], v[46:49], v[108:111]
	v_mfma_f32_16x16x32_bf16 v[54:57], v[70:73], v[26:29], v[54:57]
	v_mfma_f32_16x16x32_bf16 v[58:61], v[70:73], v[42:45], v[58:61]
	s_waitcnt vmcnt(4)
	v_mfma_f32_16x16x32_bf16 v[66:69], v[70:73], v[50:53], v[66:69]
	s_nop 4
	v_mov_b32_e32 v70, v54
	v_mov_b32_e32 v71, v58
	v_mov_b32_e32 v72, v62
	v_mov_b32_e32 v83, v58
	v_mov_b32_e32 v73, v66
	v_pk_add_f32 v[70:71], v[70:71], v[72:73]
	v_mov_b32_e32 v72, v54
	v_add_f32_e32 v70, v70, v71
	s_nop 1
	v_mov_b32_e32 v73, v62
	v_mov_b32_e32 v82, v66
	s_waitcnt lgkmcnt(0)
	v_add_f32_dpp v70, v70, v70 quad_perm:[1,0,3,2] row_mask:0xf bank_mask:0xf
	s_nop 1
	s_waitcnt lgkmcnt(0)
	v_add_f32_dpp v70, v70, v70 quad_perm:[2,3,0,1] row_mask:0xf bank_mask:0xf
	s_nop 1
	s_waitcnt lgkmcnt(0)
	v_add_f32_dpp v70, v70, v70 row_half_mirror row_mask:0xf bank_mask:0xf
	s_nop 1
	s_waitcnt lgkmcnt(0)
	v_add_f32_dpp v70, v70, v70 row_mirror row_mask:0xf bank_mask:0xf
	v_mul_f32_e32 v70, 0x3c800000, v70
	v_cndmask_b32_e32 v70, 0, v70, vcc
	v_pk_add_f32 v[72:73], v[72:73], v[70:71] op_sel_hi:[1,0] neg_lo:[0,1] neg_hi:[0,1]
	v_pk_add_f32 v[70:71], v[82:83], v[70:71] op_sel_hi:[1,0] neg_lo:[0,1] neg_hi:[0,1]
	v_pk_mul_f32 v[80:81], v[72:73], v[72:73]
	v_pk_mul_f32 v[82:83], v[70:71], v[70:71]
	v_add_f32_e32 v54, v80, v81
	v_add_f32_e32 v54, v83, v54
	v_add_f32_e32 v54, v82, v54
	s_nop 1
	s_waitcnt lgkmcnt(0)
	v_add_f32_dpp v54, v54, v54 quad_perm:[1,0,3,2] row_mask:0xf bank_mask:0xf
	s_nop 1
	s_waitcnt lgkmcnt(0)
	v_add_f32_dpp v54, v54, v54 quad_perm:[2,3,0,1] row_mask:0xf bank_mask:0xf
	s_nop 1
	s_waitcnt lgkmcnt(0)
	v_add_f32_dpp v54, v54, v54 row_half_mirror row_mask:0xf bank_mask:0xf
	s_nop 1
	s_waitcnt lgkmcnt(0)
	v_add_f32_dpp v54, v54, v54 row_mirror row_mask:0xf bank_mask:0xf
	v_fmamk_f32 v54, v54, 0x3c800000, v107
	v_cmp_gt_f32_e64 s[0:1], s3, v54
	v_mul_f32_e32 v58, 0x4b800000, v54
	s_nop 0
	v_cndmask_b32_e64 v54, v54, v58, s[0:1]
	v_rsq_f32_e32 v54, v54
	s_nop 0
	v_mul_f32_e32 v58, 0x45800000, v54
	v_cndmask_b32_e64 v58, v54, v58, s[0:1]
	v_mul_lo_u32 v54, v84, s34
	v_add3_u32 v54, v85, v95, v54
	v_mov_b32_e32 v62, v134
	s_nop 0
	s_waitcnt lgkmcnt(0)
	v_lshlrev_b32_e32 v62, 16, v62
	v_mul_f32_e32 v66, 0xbfb8aa3b, v62
	v_exp_f32_e32 v66, v66
	s_nop 0
	v_add_f32_e32 v66, 1.0, v66
	v_rcp_f32_e32 v66, v66
	s_nop 0
	v_mul_f32_e32 v62, v66, v62
	v_mul_f32_e32 v66, v72, v58
	s_waitcnt vmcnt(3)
	v_mul_f32_e32 v66, v106, v66
	v_mul_f32_e32 v62, v62, v66
	v_cvt_pk_bf16_f32 v62, v62, v157
	ds_write_b16 v54, v62
	v_mov_b32_e32 v62, v135
	s_nop 0
	s_waitcnt lgkmcnt(0)
	v_lshlrev_b32_e32 v62, 16, v62
	v_mul_f32_e32 v66, 0xbfb8aa3b, v62
	v_exp_f32_e32 v66, v66
	s_nop 0
	v_add_f32_e32 v66, 1.0, v66
	v_rcp_f32_e32 v66, v66
	s_nop 0
	v_mul_f32_e32 v62, v66, v62
	v_mul_f32_e32 v66, v73, v58
	s_waitcnt vmcnt(2)
	v_mul_f32_e32 v66, v103, v66
	v_mul_f32_e32 v62, v62, v66
	v_cvt_pk_bf16_f32 v62, v62, v157
	ds_write_b16 v54, v62 offset:32
	v_mov_b32_e32 v62, v136
	s_nop 0
	s_waitcnt lgkmcnt(0)
	v_lshlrev_b32_e32 v62, 16, v62
	v_mul_f32_e32 v66, 0xbfb8aa3b, v62
	v_exp_f32_e32 v66, v66
	s_nop 0
	v_add_f32_e32 v66, 1.0, v66
	v_rcp_f32_e32 v66, v66
	s_nop 0
	v_mul_f32_e32 v62, v66, v62
	v_mul_f32_e32 v66, v71, v58
	s_waitcnt vmcnt(1)
	v_mul_f32_e32 v66, v101, v66
	v_mul_f32_e32 v62, v62, v66
	v_cvt_pk_bf16_f32 v62, v62, v157
	ds_write_b16 v54, v62 offset:64
	v_mov_b32_e32 v62, v137
	s_nop 0
	v_mul_f32_e32 v58, v70, v58
	s_waitcnt vmcnt(0)
	s_add_i32 s98, s10, s18
	s_cmpk_ge_u32 s98, 0x600
	s_cbranch_scc1 .LpfO_done
	s_lshr_b32 s99, s98, 9
	s_and_b32 s98, s98, 0x1ff
	s_lshr_b32 s100, s98, 7
	s_and_b32 s98, s98, 0x7f
	s_lshl_b32 s101, s99, 2
	s_add_u32 s101, s101, s100
	s_lshl_b32 s101, s101, 9
	s_add_u32 s101, s101, s98
	s_lshl_b32 s101, s101, 13
	s_cmp_eq_u32 s99, 2
	s_mul_i32 s99, s99, 0xc00
	s_cselect_b32 s32, 0x400, 0
	s_sub_u32 s99, s99, s32
	s_add_u32 s99, s99, 0x600
	s_lshl_b32 s100, s100, 13
	s_lshl_b32 s98, s98, 6
	s_add_u32 s98, s98, s100
	s_mul_i32 s98, s98, 0x1c00
	s_add_u32 s98, s98, s99
	v_and_b32_e32 v237, 0xff, v224
	v_lshrrev_b32_e32 v238, 2, v237
	v_and_b32_e32 v239, 3, v237
	v_lshlrev_b32_e32 v239, 7, v239
	v_mad_u32_u24 v238, v238, s71, v239
	v_lshrrev_b32_e32 v239, 6, v237
	v_and_b32_e32 v237, 63, v237
	v_lshlrev_b32_e32 v239, 20, v239
	v_lshl_or_b32 v237, v237, 7, v239
	v_readfirstlane_b32 s32, v224
	s_add_u32 s82, s76, s98
	s_addc_u32 s83, s77, 0
	s_cmpk_lt_u32 s32, 0x100
	s_cbranch_scc0 .LpfO_hi
	s_add_u32 s98, s101, 0x3500000
	s_add_u32 s98, s30, s98
	s_addc_u32 s99, s31, 0
	global_load_dword v234, v238, s[82:83]
	global_load_dword v234, v237, s[98:99]
	s_branch .LpfO_done

; #define LAS __attribute__((address_space(3)))
; __device__ __forceinline__ float bf2f(bf16_t b) { return __uint_as_float((unsigned)b << 16); }
; __device__ __forceinline__ bf16_t f2bf(float f) { return (bf16_t)(pk2(f, 0.f) & 0xffffu); }
; __device__ __forceinline__ float silu_acc(float x) { return x * frcp(1.0f + fexp(-x)); }
; __device__ __forceinline__ void mixer_out_phase(const Ctx& X, LAS unsigned char* lds, int layer, int tid, int wave, int lane) {
;     ...
;             for (int j = 0; j < 4; ++j) {
;                 float sm = (acc[0][j] + acc[1][j]) + (acc[2][j] + acc[3][j]);
;                 sm += __shfl_xor(sm, 1); sm += __shfl_xor(sm, 2); sm += __shfl_xor(sm, 4); sm += __shfl_xor(sm, 8);
;                 const float mu = mixer == 0 ? sm * (1.f / 64.f) : 0.f;
;                 float d[4], s2 = 0.f;
; #pragma unroll
;                 for (int ct = 0; ct < 4; ++ct) { d[ct] = acc[ct][j] - mu; s2 += d[ct] * d[ct]; }
;                 s2 += __shfl_xor(s2, 1); s2 += __shfl_xor(s2, 2); s2 += __shfl_xor(s2, 4); s2 += __shfl_xor(s2, 8);
;                 const float rs = rsqrtf(s2 * (1.f / 64.f) + (mixer == 0 ? 1e-5f : 1e-6f));
;                 const int ii = 16 * (2 * half + rt) + 4 * q + j;
; #pragma unroll
;                 for (int ct = 0; ct < 4; ++ct) { LAS bf16_t* gp = GT + ii * GP + h * 64 + 16 * ct + r;
;                     const float y = d[ct] * rs * wv[ct] * silu_acc(bf2f(*gp));
;                     *gp = on ? f2bf(y) : (bf16_t)0; }
.LpfO_done:
	v_mul_f32_e32 v58, v99, v58
	s_waitcnt lgkmcnt(0)
	v_lshlrev_b32_e32 v62, 16, v62
	v_mul_f32_e32 v66, 0xbfb8aa3b, v62
	v_exp_f32_e32 v66, v66
	s_nop 0
	v_add_f32_e32 v66, 1.0, v66
	v_rcp_f32_e32 v66, v66
	s_nop 0
	v_mul_f32_e32 v62, v66, v62
	v_mul_f32_e32 v58, v62, v58
	v_cvt_pk_bf16_f32 v58, v58, v157
	ds_write_b16 v54, v58 offset:96
	v_mov_b32_e32 v58, v55
	v_mov_b32_e32 v66, v63
	v_pk_add_f32 v[70:71], v[58:59], v[66:67]
	s_nop 0
	v_add_f32_e32 v58, v70, v71
	s_nop 1
	s_waitcnt lgkmcnt(0)
	v_add_f32_dpp v58, v58, v58 quad_perm:[1,0,3,2] row_mask:0xf bank_mask:0xf
	s_nop 1
	s_waitcnt lgkmcnt(0)
	v_add_f32_dpp v58, v58, v58 quad_perm:[2,3,0,1] row_mask:0xf bank_mask:0xf
	s_nop 1
	s_waitcnt lgkmcnt(0)
	v_add_f32_dpp v58, v58, v58 row_half_mirror row_mask:0xf bank_mask:0xf
	s_nop 1
	s_waitcnt lgkmcnt(0)
	v_add_f32_dpp v58, v58, v58 row_mirror row_mask:0xf bank_mask:0xf
	v_mul_f32_e32 v58, 0x3c800000, v58
	v_cndmask_b32_e32 v66, 0, v58, vcc
	v_mov_b32_e32 v62, v55
	v_pk_add_f32 v[62:63], v[62:63], v[66:67] op_sel_hi:[1,0] neg_lo:[0,1] neg_hi:[0,1]
	v_mov_b32_e32 v58, v67
	v_pk_mul_f32 v[70:71], v[62:63], v[62:63]
	v_pk_add_f32 v[58:59], v[58:59], v[66:67] op_sel_hi:[1,0] neg_lo:[0,1] neg_hi:[0,1]
	v_add_f32_e32 v55, v70, v71
	v_pk_mul_f32 v[66:67], v[58:59], v[58:59]
	v_mov_b32_e32 v70, v68
	v_add_f32_e32 v55, v67, v55
	v_add_f32_e32 v55, v66, v55
	s_nop 1
	v_mov_b32_e32 v71, v60
	s_waitcnt lgkmcnt(0)
	v_add_f32_dpp v55, v55, v55 quad_perm:[1,0,3,2] row_mask:0xf bank_mask:0xf
	s_nop 1
	s_waitcnt lgkmcnt(0)
	v_add_f32_dpp v55, v55, v55 quad_perm:[2,3,0,1] row_mask:0xf bank_mask:0xf
	s_nop 1
	s_waitcnt lgkmcnt(0)
	v_add_f32_dpp v55, v55, v55 row_half_mirror row_mask:0xf bank_mask:0xf
	s_nop 1
	s_waitcnt lgkmcnt(0)
	v_add_f32_dpp v55, v55, v55 row_mirror row_mask:0xf bank_mask:0xf
	v_fmamk_f32 v55, v55, 0x3c800000, v107
	v_cmp_gt_f32_e64 s[0:1], s3, v55
	v_mul_f32_e32 v66, 0x4b800000, v55
	s_nop 0
	v_cndmask_b32_e64 v55, v55, v66, s[0:1]
	v_rsq_f32_e32 v55, v55
	s_nop 0
	v_mul_f32_e32 v66, 0x45800000, v55
	v_cndmask_b32_e64 v55, v55, v66, s[0:1]
	v_mov_b32_e32 v66, v138
	s_nop 0
	v_mul_f32_e32 v62, v62, v55
	v_mul_f32_e32 v62, v106, v62
	v_mul_f32_e32 v63, v63, v55
	v_mul_f32_e32 v63, v103, v63
	s_waitcnt lgkmcnt(0)
	v_lshlrev_b32_e32 v66, 16, v66
	v_mul_f32_e32 v67, 0xbfb8aa3b, v66
	v_exp_f32_e32 v67, v67
	v_mul_f32_e32 v59, v59, v55
	v_mul_f32_e32 v59, v101, v59
	v_mul_f32_e32 v55, v58, v55
	v_add_f32_e32 v67, 1.0, v67
	v_rcp_f32_e32 v67, v67
	v_mul_f32_e32 v55, v99, v55
	v_mov_b32_e32 v58, v56
	v_mul_f32_e32 v66, v67, v66
	v_mul_f32_e32 v62, v66, v62
	v_cvt_pk_bf16_f32 v62, v62, v157
	ds_write_b16 v54, v62 offset:528
	v_mov_b32_e32 v62, v139
	s_nop 0
	s_waitcnt lgkmcnt(0)
	v_lshlrev_b32_e32 v62, 16, v62
	v_mul_f32_e32 v66, 0xbfb8aa3b, v62
	v_exp_f32_e32 v66, v66
	s_nop 0
	v_add_f32_e32 v66, 1.0, v66
	v_rcp_f32_e32 v66, v66
	s_nop 0
	v_mul_f32_e32 v62, v66, v62
	v_mul_f32_e32 v62, v62, v63
	v_cvt_pk_bf16_f32 v62, v62, v157
	ds_write_b16 v54, v62 offset:560
	v_mov_b32_e32 v62, v140
	s_nop 0
	s_waitcnt lgkmcnt(0)
	v_lshlrev_b32_e32 v62, 16, v62
	v_mul_f32_e32 v63, 0xbfb8aa3b, v62
	v_exp_f32_e32 v63, v63
	s_nop 0
	v_add_f32_e32 v63, 1.0, v63
	v_rcp_f32_e32 v63, v63
	s_nop 0
	v_mul_f32_e32 v62, v63, v62
	v_mul_f32_e32 v59, v62, v59
	v_cvt_pk_bf16_f32 v59, v59, v157
	ds_write_b16 v54, v59 offset:592
	v_mov_b32_e32 v59, v141
	s_nop 0
	v_mov_b32_e32 v63, v68
	v_mov_b32_e32 v68, v65
	s_waitcnt lgkmcnt(0)
	v_lshlrev_b32_e32 v59, 16, v59
	v_mul_f32_e32 v62, 0xbfb8aa3b, v59
	v_exp_f32_e32 v62, v62
	s_nop 0
	v_add_f32_e32 v62, 1.0, v62
	v_rcp_f32_e32 v62, v62
	s_nop 0
	v_mul_f32_e32 v59, v62, v59
	v_mul_f32_e32 v55, v55, v59
	v_mov_b32_e32 v59, v60
	v_mov_b32_e32 v62, v64
	v_cvt_pk_bf16_f32 v55, v55, v157
	v_pk_add_f32 v[58:59], v[58:59], v[62:63]
	ds_write_b16 v54, v55 offset:624
	v_add_f32_e32 v55, v58, v59
	s_nop 1
	v_mov_b32_e32 v62, v56
	v_mov_b32_e32 v63, v64
	v_mov_b32_e32 v64, v57
	s_waitcnt lgkmcnt(0)
	v_add_f32_dpp v55, v55, v55 quad_perm:[1,0,3,2] row_mask:0xf bank_mask:0xf
	s_nop 1
	s_waitcnt lgkmcnt(0)
	v_add_f32_dpp v55, v55, v55 quad_perm:[2,3,0,1] row_mask:0xf bank_mask:0xf
	s_nop 1
	s_waitcnt lgkmcnt(0)
	v_add_f32_dpp v55, v55, v55 row_half_mirror row_mask:0xf bank_mask:0xf
	s_nop 1
	s_waitcnt lgkmcnt(0)
	v_add_f32_dpp v55, v55, v55 row_mirror row_mask:0xf bank_mask:0xf
	v_mul_f32_e32 v55, 0x3c800000, v55
	v_cndmask_b32_e32 v58, 0, v55, vcc
	v_pk_add_f32 v[62:63], v[62:63], v[58:59] op_sel_hi:[1,0] neg_lo:[0,1] neg_hi:[0,1]
	v_pk_add_f32 v[58:59], v[70:71], v[58:59] op_sel_hi:[1,0] neg_lo:[0,1] neg_hi:[0,1]
	v_pk_mul_f32 v[66:67], v[62:63], v[62:63]
	v_pk_mul_f32 v[70:71], v[58:59], v[58:59]
	v_add_f32_e32 v55, v66, v67
	v_add_f32_e32 v55, v71, v55
	v_add_f32_e32 v55, v70, v55
	s_nop 1
	v_lshlrev_b32_e32 v66, 16, v17
	v_and_b32_e32 v67, 0xffff0000, v17
	s_waitcnt lgkmcnt(0)
	v_add_f32_dpp v55, v55, v55 quad_perm:[1,0,3,2] row_mask:0xf bank_mask:0xf
	s_nop 1
	s_waitcnt lgkmcnt(0)
	v_add_f32_dpp v55, v55, v55 quad_perm:[2,3,0,1] row_mask:0xf bank_mask:0xf
	s_nop 1
	s_waitcnt lgkmcnt(0)
	v_add_f32_dpp v55, v55, v55 row_half_mirror row_mask:0xf bank_mask:0xf
	s_nop 1
	s_waitcnt lgkmcnt(0)
	v_add_f32_dpp v55, v55, v55 row_mirror row_mask:0xf bank_mask:0xf
	v_fmamk_f32 v55, v55, 0x3c800000, v107
	v_cmp_gt_f32_e64 s[0:1], s3, v55
	v_mul_f32_e32 v56, 0x4b800000, v55
	s_nop 0
	v_cndmask_b32_e64 v55, v55, v56, s[0:1]
	v_rsq_f32_e32 v55, v55
	s_nop 0
	v_mul_f32_e32 v56, 0x45800000, v55
	v_cndmask_b32_e64 v55, v55, v56, s[0:1]
	v_mov_b32_e32 v56, v142
	s_nop 0
	v_mul_f32_e32 v59, v59, v55
	v_mul_f32_e32 v59, v101, v59
	s_waitcnt lgkmcnt(0)
; #define LAS __attribute__((address_space(3)))
; __device__ __forceinline__ float bf_lo(unsigned u) { return __uint_as_float(u << 16); }
; __device__ __forceinline__ float bf_hi(unsigned u) { return __uint_as_float(u & 0xffff0000u); }
; __device__ __forceinline__ float bf2f(bf16_t b) { return __uint_as_float((unsigned)b << 16); }
; __device__ __forceinline__ bf16_t f2bf(float f) { return (bf16_t)(pk2(f, 0.f) & 0xffffu); }
; __device__ __forceinline__ float silu_acc(float x) { return x * frcp(1.0f + fexp(-x)); }
; __device__ __forceinline__ void mixer_out_phase(const Ctx& X, LAS unsigned char* lds, int layer, int tid, int wave, int lane) {
;     ...
;         for (int rt = 0; rt < 2; ++rt) {
;             f32x4 acc[4];
;             acc[0] = (f32x4){bf_lo(ov[rt][0].x), bf_hi(ov[rt][0].x), bf_lo(ov[rt][0].y), bf_hi(ov[rt][0].y)}; acc[1] = (f32x4){bf_lo(ov[rt][0].z), bf_hi(ov[rt][0].z), bf_lo(ov[rt][0].w), bf_hi(ov[rt][0].w)};
;             acc[2] = (f32x4){bf_lo(ov[rt][1].x), bf_hi(ov[rt][1].x), bf_lo(ov[rt][1].y), bf_hi(ov[rt][1].y)}; acc[3] = (f32x4){bf_lo(ov[rt][1].z), bf_hi(ov[rt][1].z), bf_lo(ov[rt][1].w), bf_hi(ov[rt][1].w)};
; #pragma unroll
;             for (int ct = 0; ct < 4; ++ct)
; #pragma unroll
;                 for (int ks = 0; ks < 2; ++ks) acc[ct] = __builtin_amdgcn_mfma_f32_16x16x32_bf16(a[rt][ks], bb[ct][ks], acc[ct], 0, 0, 0);
; #pragma unroll
;             for (int j = 0; j < 4; ++j) {
;                 float sm = (acc[0][j] + acc[1][j]) + (acc[2][j] + acc[3][j]);
;                 sm += __shfl_xor(sm, 1); sm += __shfl_xor(sm, 2); sm += __shfl_xor(sm, 4); sm += __shfl_xor(sm, 8);
;                 const float mu = mixer == 0 ? sm * (1.f / 64.f) : 0.f;
;                 float d[4], s2 = 0.f;
; #pragma unroll
;                 for (int ct = 0; ct < 4; ++ct) { d[ct] = acc[ct][j] - mu; s2 += d[ct] * d[ct]; }
;                 s2 += __shfl_xor(s2, 1); s2 += __shfl_xor(s2, 2); s2 += __shfl_xor(s2, 4); s2 += __shfl_xor(s2, 8);
;                 const float rs = rsqrtf(s2 * (1.f / 64.f) + (mixer == 0 ? 1e-5f : 1e-6f));
;                 const int ii = 16 * (2 * half + rt) + 4 * q + j;
; #pragma unroll
;                 for (int ct = 0; ct < 4; ++ct) { LAS bf16_t* gp = GT + ii * GP + h * 64 + 16 * ct + r;
;                     const float y = d[ct] * rs * wv[ct] * silu_acc(bf2f(*gp));
;                     *gp = on ? f2bf(y) : (bf16_t)0; }
	v_lshlrev_b32_e32 v56, 16, v56
	v_mul_f32_e32 v60, 0xbfb8aa3b, v56
	v_exp_f32_e32 v60, v60
	s_nop 0
	v_add_f32_e32 v60, 1.0, v60
	v_rcp_f32_e32 v60, v60
	s_nop 0
	v_mul_f32_e32 v56, v60, v56
	v_mul_f32_e32 v60, v62, v55
	v_mul_f32_e32 v60, v106, v60
	v_mul_f32_e32 v56, v56, v60
	v_cvt_pk_bf16_f32 v56, v56, v157
	ds_write_b16 v54, v56 offset:1056
	v_mov_b32_e32 v56, v143
	s_nop 0
	s_waitcnt lgkmcnt(0)
	v_lshlrev_b32_e32 v56, 16, v56
	v_mul_f32_e32 v60, 0xbfb8aa3b, v56
	v_exp_f32_e32 v60, v60
	s_nop 0
	v_add_f32_e32 v60, 1.0, v60
	v_rcp_f32_e32 v60, v60
	s_nop 0
	v_mul_f32_e32 v56, v60, v56
	v_mul_f32_e32 v60, v63, v55
	v_mul_f32_e32 v60, v103, v60
	v_mul_f32_e32 v56, v56, v60
	v_cvt_pk_bf16_f32 v56, v56, v157
	ds_write_b16 v54, v56 offset:1088
	v_mov_b32_e32 v56, v144
	s_nop 0
	v_mul_f32_e32 v55, v58, v55
	v_mul_f32_e32 v55, v99, v55
	s_waitcnt lgkmcnt(0)
	v_lshlrev_b32_e32 v56, 16, v56
	v_mul_f32_e32 v60, 0xbfb8aa3b, v56
	v_exp_f32_e32 v60, v60
	s_nop 0
	v_add_f32_e32 v60, 1.0, v60
	v_rcp_f32_e32 v60, v60
	s_nop 0
	v_mul_f32_e32 v56, v60, v56
	v_mul_f32_e32 v56, v56, v59
	v_cvt_pk_bf16_f32 v56, v56, v157
	ds_write_b16 v54, v56 offset:1120
	v_mov_b32_e32 v56, v145
	s_nop 0
	v_mov_b32_e32 v60, v57
	s_waitcnt lgkmcnt(0)
	v_lshlrev_b32_e32 v56, 16, v56
	v_mul_f32_e32 v59, 0xbfb8aa3b, v56
	v_exp_f32_e32 v59, v59
	s_nop 0
	v_add_f32_e32 v59, 1.0, v59
	v_rcp_f32_e32 v59, v59
	s_nop 0
	v_mul_f32_e32 v56, v59, v56
	v_mul_f32_e32 v55, v55, v56
	v_cvt_pk_bf16_f32 v55, v55, v157
	v_pk_add_f32 v[58:59], v[60:61], v[68:69]
	ds_write_b16 v54, v55 offset:1152
	v_add_f32_e32 v55, v58, v59
	s_nop 1
	v_mov_b32_e32 v60, v69
	s_waitcnt lgkmcnt(0)
	v_add_f32_dpp v55, v55, v55 quad_perm:[1,0,3,2] row_mask:0xf bank_mask:0xf
	s_nop 1
	s_waitcnt lgkmcnt(0)
	v_add_f32_dpp v55, v55, v55 quad_perm:[2,3,0,1] row_mask:0xf bank_mask:0xf
	s_nop 1
	s_waitcnt lgkmcnt(0)
	v_add_f32_dpp v55, v55, v55 row_half_mirror row_mask:0xf bank_mask:0xf
	s_nop 1
	s_waitcnt lgkmcnt(0)
	v_add_f32_dpp v55, v55, v55 row_mirror row_mask:0xf bank_mask:0xf
	v_mul_f32_e32 v55, 0x3c800000, v55
	v_cndmask_b32_e32 v56, 0, v55, vcc
	v_pk_add_f32 v[58:59], v[64:65], v[56:57] op_sel_hi:[1,0] neg_lo:[0,1] neg_hi:[0,1]
	v_pk_add_f32 v[56:57], v[60:61], v[56:57] op_sel_hi:[1,0] neg_lo:[0,1] neg_hi:[0,1]
	v_pk_mul_f32 v[62:63], v[58:59], v[58:59]
	v_pk_mul_f32 v[60:61], v[56:57], v[56:57]
	v_add_f32_e32 v55, v62, v63
	v_add_f32_e32 v55, v61, v55
	v_add_f32_e32 v55, v60, v55
	s_nop 1
	v_lshlrev_b32_e32 v62, 16, v15
	v_and_b32_e32 v63, 0xffff0000, v15
	v_lshlrev_b32_e32 v64, 16, v16
	v_and_b32_e32 v65, 0xffff0000, v16
	s_waitcnt lgkmcnt(0)
	v_add_f32_dpp v55, v55, v55 quad_perm:[1,0,3,2] row_mask:0xf bank_mask:0xf
	s_nop 1
	s_waitcnt lgkmcnt(0)
	v_add_f32_dpp v55, v55, v55 quad_perm:[2,3,0,1] row_mask:0xf bank_mask:0xf
	s_nop 1
	s_waitcnt lgkmcnt(0)
	v_add_f32_dpp v55, v55, v55 row_half_mirror row_mask:0xf bank_mask:0xf
	s_nop 1
	s_waitcnt lgkmcnt(0)
	v_add_f32_dpp v55, v55, v55 row_mirror row_mask:0xf bank_mask:0xf
	v_fmamk_f32 v55, v55, 0x3c800000, v107
	v_cmp_gt_f32_e64 s[0:1], s3, v55
	v_mul_f32_e32 v60, 0x4b800000, v55
	s_nop 0
	v_cndmask_b32_e64 v55, v55, v60, s[0:1]
	v_rsq_f32_e32 v55, v55
	s_nop 0
	v_mul_f32_e32 v60, 0x45800000, v55
	v_cndmask_b32_e64 v55, v55, v60, s[0:1]
	v_mov_b32_e32 v60, v147
	s_nop 0
	v_mul_f32_e32 v58, v58, v55
	v_mul_f32_e32 v58, v106, v58
	v_mul_f32_e32 v59, v59, v55
	v_mul_f32_e32 v59, v103, v59
	s_waitcnt lgkmcnt(0)
	v_lshlrev_b32_e32 v60, 16, v60
	v_mul_f32_e32 v61, 0xbfb8aa3b, v60
	v_exp_f32_e32 v61, v61
	v_mul_f32_e32 v57, v57, v55
	v_mul_f32_e32 v57, v101, v57
	v_mul_f32_e32 v55, v56, v55
	v_add_f32_e32 v61, 1.0, v61
	v_rcp_f32_e32 v61, v61
	v_mul_f32_e32 v55, v99, v55
	v_lshlrev_b32_e32 v56, 16, v18
	v_mul_f32_e32 v60, v61, v60
	v_mul_f32_e32 v58, v60, v58
	v_cvt_pk_bf16_f32 v58, v58, v157
	ds_write_b16 v54, v58 offset:1584
	v_mov_b32_e32 v58, v148
	s_nop 0
	v_and_b32_e32 v61, 0xffff0000, v14
	s_waitcnt lgkmcnt(0)
	v_lshlrev_b32_e32 v58, 16, v58
	v_mul_f32_e32 v60, 0xbfb8aa3b, v58
	v_exp_f32_e32 v60, v60
	s_nop 0
	v_add_f32_e32 v60, 1.0, v60
	v_rcp_f32_e32 v60, v60
	s_nop 0
	v_mul_f32_e32 v58, v60, v58
	v_mul_f32_e32 v58, v58, v59
	v_cvt_pk_bf16_f32 v58, v58, v157
	ds_write_b16 v54, v58 offset:1616
	v_mov_b32_e32 v58, v149
	s_nop 0
	v_lshlrev_b32_e32 v60, 16, v14
	s_waitcnt lgkmcnt(0)
	v_lshlrev_b32_e32 v58, 16, v58
	v_mul_f32_e32 v59, 0xbfb8aa3b, v58
	v_exp_f32_e32 v59, v59
	s_nop 0
	v_add_f32_e32 v59, 1.0, v59
	v_rcp_f32_e32 v59, v59
	s_nop 0
	v_mul_f32_e32 v58, v59, v58
	v_mul_f32_e32 v57, v58, v57
	v_cvt_pk_bf16_f32 v57, v57, v157
	ds_write_b16 v54, v57 offset:1648
	v_mov_b32_e32 v57, v150
	s_nop 0
	v_and_b32_e32 v59, 0xffff0000, v19
	s_waitcnt lgkmcnt(0)
	v_lshlrev_b32_e32 v57, 16, v57
	v_mul_f32_e32 v58, 0xbfb8aa3b, v57
	v_exp_f32_e32 v58, v58
	s_nop 0
	v_add_f32_e32 v58, 1.0, v58
	v_rcp_f32_e32 v58, v58
	s_nop 0
	v_mul_f32_e32 v57, v58, v57
	v_mul_f32_e32 v55, v55, v57
	v_and_b32_e32 v57, 0xffff0000, v18
	v_lshlrev_b32_e32 v58, 16, v19
	v_lshlrev_b32_e32 v18, 16, v20
	v_and_b32_e32 v19, 0xffff0000, v20
	v_lshlrev_b32_e32 v20, 16, v21
	v_and_b32_e32 v21, 0xffff0000, v21
	v_mfma_f32_16x16x32_bf16 v[14:17], v[6:9], v[22:25], v[56:59]
	v_cvt_pk_bf16_f32 v55, v55, v157
	ds_write_b16 v54, v55 offset:1680
	v_mfma_f32_16x16x32_bf16 v[18:21], v[6:9], v[30:33], v[18:21]
	v_mfma_f32_16x16x32_bf16 v[22:25], v[10:13], v[34:37], v[18:21]
	v_mfma_f32_16x16x32_bf16 v[18:21], v[6:9], v[38:41], v[60:63]
	v_mfma_f32_16x16x32_bf16 v[6:9], v[6:9], v[46:49], v[64:67]
	v_mfma_f32_16x16x32_bf16 v[14:17], v[10:13], v[26:29], v[14:17]
	v_mfma_f32_16x16x32_bf16 v[18:21], v[10:13], v[42:45], v[18:21]
	v_mfma_f32_16x16x32_bf16 v[6:9], v[10:13], v[50:53], v[6:9]
	s_nop 5
	v_mov_b32_e32 v10, v14
	v_mov_b32_e32 v11, v18
	v_mov_b32_e32 v12, v22
	v_mov_b32_e32 v29, v18
	v_mov_b32_e32 v13, v6
	v_pk_add_f32 v[10:11], v[10:11], v[12:13]
	v_mov_b32_e32 v12, v14
	v_add_f32_e32 v10, v10, v11
	s_nop 1
	v_mov_b32_e32 v13, v22
	v_mov_b32_e32 v28, v6
	v_mov_b32_e32 v22, v15
	s_waitcnt lgkmcnt(0)
; #define LAS __attribute__((address_space(3)))
; __device__ __forceinline__ float bf2f(bf16_t b) { return __uint_as_float((unsigned)b << 16); }
; __device__ __forceinline__ bf16_t f2bf(float f) { return (bf16_t)(pk2(f, 0.f) & 0xffffu); }
; __device__ __forceinline__ float silu_acc(float x) { return x * frcp(1.0f + fexp(-x)); }
; __device__ __forceinline__ void mixer_out_phase(const Ctx& X, LAS unsigned char* lds, int layer, int tid, int wave, int lane) {
;     ...
;             for (int j = 0; j < 4; ++j) {
;                 float sm = (acc[0][j] + acc[1][j]) + (acc[2][j] + acc[3][j]);
;                 sm += __shfl_xor(sm, 1); sm += __shfl_xor(sm, 2); sm += __shfl_xor(sm, 4); sm += __shfl_xor(sm, 8);
;                 const float mu = mixer == 0 ? sm * (1.f / 64.f) : 0.f;
;                 float d[4], s2 = 0.f;
; #pragma unroll
;                 for (int ct = 0; ct < 4; ++ct) { d[ct] = acc[ct][j] - mu; s2 += d[ct] * d[ct]; }
;                 s2 += __shfl_xor(s2, 1); s2 += __shfl_xor(s2, 2); s2 += __shfl_xor(s2, 4); s2 += __shfl_xor(s2, 8);
;                 const float rs = rsqrtf(s2 * (1.f / 64.f) + (mixer == 0 ? 1e-5f : 1e-6f));
;                 const int ii = 16 * (2 * half + rt) + 4 * q + j;
; #pragma unroll
;                 for (int ct = 0; ct < 4; ++ct) { LAS bf16_t* gp = GT + ii * GP + h * 64 + 16 * ct + r;
;                     const float y = d[ct] * rs * wv[ct] * silu_acc(bf2f(*gp));
;                     *gp = on ? f2bf(y) : (bf16_t)0; }
	v_add_f32_dpp v10, v10, v10 quad_perm:[1,0,3,2] row_mask:0xf bank_mask:0xf
	s_nop 1
	s_waitcnt lgkmcnt(0)
	v_add_f32_dpp v10, v10, v10 quad_perm:[2,3,0,1] row_mask:0xf bank_mask:0xf
	s_nop 1
	s_waitcnt lgkmcnt(0)
	v_add_f32_dpp v10, v10, v10 row_half_mirror row_mask:0xf bank_mask:0xf
	s_nop 1
	s_waitcnt lgkmcnt(0)
	v_add_f32_dpp v10, v10, v10 row_mirror row_mask:0xf bank_mask:0xf
	v_mul_f32_e32 v10, 0x3c800000, v10
	v_cndmask_b32_e32 v10, 0, v10, vcc
	v_pk_add_f32 v[12:13], v[12:13], v[10:11] op_sel_hi:[1,0] neg_lo:[0,1] neg_hi:[0,1]
	v_pk_add_f32 v[10:11], v[28:29], v[10:11] op_sel_hi:[1,0] neg_lo:[0,1] neg_hi:[0,1]
	v_pk_mul_f32 v[26:27], v[12:13], v[12:13]
	v_pk_mul_f32 v[28:29], v[10:11], v[10:11]
	v_add_f32_e32 v6, v26, v27
	v_add_f32_e32 v6, v29, v6
	v_add_f32_e32 v6, v28, v6
	s_nop 1
	s_waitcnt lgkmcnt(0)
	v_add_f32_dpp v6, v6, v6 quad_perm:[1,0,3,2] row_mask:0xf bank_mask:0xf
	s_nop 1
	s_waitcnt lgkmcnt(0)
	v_add_f32_dpp v6, v6, v6 quad_perm:[2,3,0,1] row_mask:0xf bank_mask:0xf
	s_nop 1
	s_waitcnt lgkmcnt(0)
	v_add_f32_dpp v6, v6, v6 row_half_mirror row_mask:0xf bank_mask:0xf
	s_nop 1
	s_waitcnt lgkmcnt(0)
	v_add_f32_dpp v6, v6, v6 row_mirror row_mask:0xf bank_mask:0xf
	v_fmamk_f32 v6, v6, 0x3c800000, v107
	v_cmp_gt_f32_e64 s[0:1], s3, v6
	v_mul_f32_e32 v14, 0x4b800000, v6
	s_nop 0
	v_cndmask_b32_e64 v6, v6, v14, s[0:1]
	v_rsq_f32_e32 v6, v6
	s_nop 0
	v_mul_f32_e32 v14, 0x45800000, v6
	v_cndmask_b32_e64 v6, v6, v14, s[0:1]
	v_mov_b32_e32 v14, v151
	s_nop 0
	v_mul_f32_e32 v12, v12, v6
	v_mul_f32_e32 v12, v106, v12
	v_mul_f32_e32 v13, v13, v6
	v_mul_f32_e32 v13, v103, v13
	s_waitcnt lgkmcnt(0)
	v_lshlrev_b32_e32 v14, 16, v14
	v_mul_f32_e32 v18, 0xbfb8aa3b, v14
	v_exp_f32_e32 v18, v18
	v_mul_f32_e32 v11, v11, v6
	v_mul_f32_e32 v11, v101, v11
	v_mul_f32_e32 v6, v10, v6
	v_add_f32_e32 v18, 1.0, v18
	v_rcp_f32_e32 v18, v18
	v_mul_f32_e32 v6, v99, v6
	v_mul_f32_e32 v14, v18, v14
	v_mul_f32_e32 v12, v14, v12
	v_cvt_pk_bf16_f32 v12, v12, v157
	ds_write_b16 v54, v12 offset:8448
	v_mov_b32_e32 v12, v152
	s_nop 0
	v_mov_b32_e32 v18, v15
	s_waitcnt lgkmcnt(0)
	v_lshlrev_b32_e32 v12, 16, v12
	v_mul_f32_e32 v14, 0xbfb8aa3b, v12
	v_exp_f32_e32 v14, v14
	s_nop 0
	v_add_f32_e32 v14, 1.0, v14
	v_rcp_f32_e32 v14, v14
	s_nop 0
	v_mul_f32_e32 v12, v14, v12
	v_mul_f32_e32 v12, v12, v13
	v_cvt_pk_bf16_f32 v12, v12, v157
	ds_write_b16 v54, v12 offset:8480
	v_mov_b32_e32 v12, v153
	s_nop 0
	s_waitcnt lgkmcnt(0)
	v_lshlrev_b32_e32 v12, 16, v12
	v_mul_f32_e32 v13, 0xbfb8aa3b, v12
	v_exp_f32_e32 v13, v13
	s_nop 0
	v_add_f32_e32 v13, 1.0, v13
	v_rcp_f32_e32 v13, v13
	s_nop 0
	v_mul_f32_e32 v12, v13, v12
	v_mul_f32_e32 v11, v12, v11
	v_cvt_pk_bf16_f32 v11, v11, v157
	ds_write_b16 v54, v11 offset:8512
	v_mov_b32_e32 v11, v154
	s_nop 0
	s_waitcnt lgkmcnt(0)
	v_lshlrev_b32_e32 v11, 16, v11
	v_mul_f32_e32 v12, 0xbfb8aa3b, v11
	v_exp_f32_e32 v12, v12
	s_nop 0
	v_add_f32_e32 v12, 1.0, v12
	v_rcp_f32_e32 v12, v12
	s_nop 0
	v_mul_f32_e32 v11, v12, v11
	v_mul_f32_e32 v6, v11, v6
	v_cvt_pk_bf16_f32 v6, v6, v157
	ds_write_b16 v54, v6 offset:8544
	v_mov_b32_e32 v6, v23
	v_pk_add_f32 v[10:11], v[18:19], v[6:7]
	v_mov_b32_e32 v18, v7
	v_add_f32_e32 v6, v10, v11
	s_nop 1
	s_waitcnt lgkmcnt(0)
	v_add_f32_dpp v6, v6, v6 quad_perm:[1,0,3,2] row_mask:0xf bank_mask:0xf
	s_nop 1
	s_waitcnt lgkmcnt(0)
	v_add_f32_dpp v6, v6, v6 quad_perm:[2,3,0,1] row_mask:0xf bank_mask:0xf
	s_nop 1
	s_waitcnt lgkmcnt(0)
	v_add_f32_dpp v6, v6, v6 row_half_mirror row_mask:0xf bank_mask:0xf
	s_nop 1
	s_waitcnt lgkmcnt(0)
	v_add_f32_dpp v6, v6, v6 row_mirror row_mask:0xf bank_mask:0xf
	v_mul_f32_e32 v6, 0x3c800000, v6
	v_cndmask_b32_e32 v6, 0, v6, vcc
	v_pk_add_f32 v[10:11], v[22:23], v[6:7] op_sel_hi:[1,0] neg_lo:[0,1] neg_hi:[0,1]
	v_pk_add_f32 v[6:7], v[18:19], v[6:7] op_sel_hi:[1,0] neg_lo:[0,1] neg_hi:[0,1]
	v_pk_mul_f32 v[12:13], v[10:11], v[10:11]
	v_pk_mul_f32 v[14:15], v[6:7], v[6:7]
	v_add_f32_e32 v12, v12, v13
	v_add_f32_e32 v12, v15, v12
	v_add_f32_e32 v12, v14, v12
	s_nop 1
	v_mov_b32_e32 v15, v20
	s_waitcnt lgkmcnt(0)
	v_add_f32_dpp v12, v12, v12 quad_perm:[1,0,3,2] row_mask:0xf bank_mask:0xf
	s_nop 1
	s_waitcnt lgkmcnt(0)
	v_add_f32_dpp v12, v12, v12 quad_perm:[2,3,0,1] row_mask:0xf bank_mask:0xf
	s_nop 1
	s_waitcnt lgkmcnt(0)
	v_add_f32_dpp v12, v12, v12 row_half_mirror row_mask:0xf bank_mask:0xf
	s_nop 1
	s_waitcnt lgkmcnt(0)
	v_add_f32_dpp v12, v12, v12 row_mirror row_mask:0xf bank_mask:0xf
	v_fmamk_f32 v12, v12, 0x3c800000, v107
	v_cmp_gt_f32_e64 s[0:1], s3, v12
	v_mul_f32_e32 v13, 0x4b800000, v12
	s_nop 0
	v_cndmask_b32_e64 v12, v12, v13, s[0:1]
	v_rsq_f32_e32 v12, v12
	s_nop 0
	v_mul_f32_e32 v13, 0x45800000, v12
	v_cndmask_b32_e64 v12, v12, v13, s[0:1]
	v_mov_b32_e32 v13, v155
	s_nop 0
	v_mul_f32_e32 v10, v10, v12
	v_mul_f32_e32 v10, v106, v10
	v_mul_f32_e32 v11, v11, v12
	v_mul_f32_e32 v11, v103, v11
	s_waitcnt lgkmcnt(0)
	v_lshlrev_b32_e32 v13, 16, v13
	v_mul_f32_e32 v14, 0xbfb8aa3b, v13
	v_exp_f32_e32 v14, v14
	v_mul_f32_e32 v7, v7, v12
	v_mul_f32_e32 v7, v101, v7
	v_mul_f32_e32 v6, v6, v12
	v_add_f32_e32 v14, 1.0, v14
	v_rcp_f32_e32 v14, v14
	v_mul_f32_e32 v6, v99, v6
	v_mul_f32_e32 v13, v14, v13
	v_mul_f32_e32 v10, v13, v10
	v_cvt_pk_bf16_f32 v10, v10, v157
	ds_write_b16 v54, v10 offset:8976
	v_mov_b32_e32 v10, v182
	s_nop 0
	v_mov_b32_e32 v14, v8
	s_waitcnt lgkmcnt(0)
	v_lshlrev_b32_e32 v10, 16, v10
	v_mul_f32_e32 v13, 0xbfb8aa3b, v10
	v_exp_f32_e32 v13, v13
	s_nop 0
	v_add_f32_e32 v13, 1.0, v13
	v_rcp_f32_e32 v13, v13
	s_nop 0
	v_mul_f32_e32 v10, v13, v10
	v_mul_f32_e32 v10, v10, v11
	v_cvt_pk_bf16_f32 v10, v10, v157
	ds_write_b16 v54, v10 offset:9008
	v_mov_b32_e32 v10, v183
	s_nop 0
	s_waitcnt lgkmcnt(0)
; #define LAS __attribute__((address_space(3)))
; __device__ __forceinline__ float bf2f(bf16_t b) { return __uint_as_float((unsigned)b << 16); }
; __device__ __forceinline__ bf16_t f2bf(float f) { return (bf16_t)(pk2(f, 0.f) & 0xffffu); }
; __device__ __forceinline__ float silu_acc(float x) { return x * frcp(1.0f + fexp(-x)); }
; __device__ __forceinline__ void mixer_out_phase(const Ctx& X, LAS unsigned char* lds, int layer, int tid, int wave, int lane) {
;     ...
;             for (int j = 0; j < 4; ++j) {
;                 float sm = (acc[0][j] + acc[1][j]) + (acc[2][j] + acc[3][j]);
;                 sm += __shfl_xor(sm, 1); sm += __shfl_xor(sm, 2); sm += __shfl_xor(sm, 4); sm += __shfl_xor(sm, 8);
;                 const float mu = mixer == 0 ? sm * (1.f / 64.f) : 0.f;
;                 float d[4], s2 = 0.f;
; #pragma unroll
;                 for (int ct = 0; ct < 4; ++ct) { d[ct] = acc[ct][j] - mu; s2 += d[ct] * d[ct]; }
;                 s2 += __shfl_xor(s2, 1); s2 += __shfl_xor(s2, 2); s2 += __shfl_xor(s2, 4); s2 += __shfl_xor(s2, 8);
;                 const float rs = rsqrtf(s2 * (1.f / 64.f) + (mixer == 0 ? 1e-5f : 1e-6f));
;                 const int ii = 16 * (2 * half + rt) + 4 * q + j;
; #pragma unroll
;                 for (int ct = 0; ct < 4; ++ct) { LAS bf16_t* gp = GT + ii * GP + h * 64 + 16 * ct + r;
;                     const float y = d[ct] * rs * wv[ct] * silu_acc(bf2f(*gp));
;                     *gp = on ? f2bf(y) : (bf16_t)0; }
	v_lshlrev_b32_e32 v10, 16, v10
	v_mul_f32_e32 v11, 0xbfb8aa3b, v10
	v_exp_f32_e32 v11, v11
	s_nop 0
	v_add_f32_e32 v11, 1.0, v11
	v_rcp_f32_e32 v11, v11
	s_nop 0
	v_mul_f32_e32 v10, v11, v10
	v_mul_f32_e32 v7, v10, v7
	v_cvt_pk_bf16_f32 v7, v7, v157
	ds_write_b16 v54, v7 offset:9040
	v_mov_b32_e32 v7, v184
	s_nop 0
	v_mov_b32_e32 v11, v8
	s_waitcnt lgkmcnt(0)
	v_lshlrev_b32_e32 v7, 16, v7
	v_mul_f32_e32 v10, 0xbfb8aa3b, v7
	v_exp_f32_e32 v10, v10
	s_nop 0
	v_add_f32_e32 v10, 1.0, v10
	v_rcp_f32_e32 v10, v10
	s_nop 0
	v_mul_f32_e32 v7, v10, v7
	v_mul_f32_e32 v6, v6, v7
	v_cvt_pk_bf16_f32 v6, v6, v157
	ds_write_b16 v54, v6 offset:9072
	v_mov_b32_e32 v6, v16
	v_mov_b32_e32 v7, v20
	v_mov_b32_e32 v10, v24
	v_pk_add_f32 v[6:7], v[6:7], v[10:11]
	v_mov_b32_e32 v10, v16
	v_add_f32_e32 v6, v6, v7
	s_nop 1
	v_mov_b32_e32 v11, v24
	v_mov_b32_e32 v20, v17
	v_mov_b32_e32 v24, v17
	s_waitcnt lgkmcnt(0)
	v_add_f32_dpp v6, v6, v6 quad_perm:[1,0,3,2] row_mask:0xf bank_mask:0xf
	s_nop 1
	s_waitcnt lgkmcnt(0)
	v_add_f32_dpp v6, v6, v6 quad_perm:[2,3,0,1] row_mask:0xf bank_mask:0xf
	s_nop 1
	s_waitcnt lgkmcnt(0)
	v_add_f32_dpp v6, v6, v6 row_half_mirror row_mask:0xf bank_mask:0xf
	s_nop 1
	s_waitcnt lgkmcnt(0)
	v_add_f32_dpp v6, v6, v6 row_mirror row_mask:0xf bank_mask:0xf
	v_mul_f32_e32 v6, 0x3c800000, v6
	v_cndmask_b32_e32 v6, 0, v6, vcc
	v_pk_add_f32 v[10:11], v[10:11], v[6:7] op_sel_hi:[1,0] neg_lo:[0,1] neg_hi:[0,1]
	v_pk_add_f32 v[6:7], v[14:15], v[6:7] op_sel_hi:[1,0] neg_lo:[0,1] neg_hi:[0,1]
	v_pk_mul_f32 v[12:13], v[10:11], v[10:11]
	v_pk_mul_f32 v[14:15], v[6:7], v[6:7]
	v_add_f32_e32 v8, v12, v13
	v_add_f32_e32 v8, v15, v8
	v_add_f32_e32 v8, v14, v8
	s_nop 1
	s_waitcnt lgkmcnt(0)
	v_add_f32_dpp v8, v8, v8 quad_perm:[1,0,3,2] row_mask:0xf bank_mask:0xf
	s_nop 1
	s_waitcnt lgkmcnt(0)
	v_add_f32_dpp v8, v8, v8 quad_perm:[2,3,0,1] row_mask:0xf bank_mask:0xf
	s_nop 1
	s_waitcnt lgkmcnt(0)
	v_add_f32_dpp v8, v8, v8 row_half_mirror row_mask:0xf bank_mask:0xf
	s_nop 1
	s_waitcnt lgkmcnt(0)
	v_add_f32_dpp v8, v8, v8 row_mirror row_mask:0xf bank_mask:0xf
	v_fmamk_f32 v8, v8, 0x3c800000, v107
	v_cmp_gt_f32_e64 s[0:1], s3, v8
	v_mul_f32_e32 v12, 0x4b800000, v8
	s_nop 0
	v_cndmask_b32_e64 v8, v8, v12, s[0:1]
	v_rsq_f32_e32 v8, v8
	s_nop 0
	v_mul_f32_e32 v12, 0x45800000, v8
	v_cndmask_b32_e64 v8, v8, v12, s[0:1]
	v_mov_b32_e32 v12, v185
	s_nop 0
	v_mul_f32_e32 v10, v10, v8
	v_mul_f32_e32 v10, v106, v10
	v_mul_f32_e32 v11, v11, v8
	v_mul_f32_e32 v11, v103, v11
	s_waitcnt lgkmcnt(0)
	v_lshlrev_b32_e32 v12, 16, v12
	v_mul_f32_e32 v13, 0xbfb8aa3b, v12
	v_exp_f32_e32 v13, v13
	v_mul_f32_e32 v7, v7, v8
	v_mul_f32_e32 v7, v101, v7
	v_mul_f32_e32 v6, v6, v8
	v_add_f32_e32 v13, 1.0, v13
	v_rcp_f32_e32 v13, v13
	v_mul_f32_e32 v6, v99, v6
	v_mov_b32_e32 v8, v25
	s_lshl_b32 s0, s11, 1
	v_mul_f32_e32 v12, v13, v12
	v_mul_f32_e32 v10, v12, v10
	v_cvt_pk_bf16_f32 v10, v10, v157
	ds_write_b16 v54, v10 offset:9504
	v_mov_b32_e32 v10, v186
	s_nop 0
	s_add_u32 s0, s60, s0
	s_addc_u32 s1, s67, 0
	s_add_i32 s10, s10, s18
	s_cmpk_lt_i32 s10, 0x600
	s_waitcnt lgkmcnt(0)
	v_lshlrev_b32_e32 v10, 16, v10
	v_mul_f32_e32 v12, 0xbfb8aa3b, v10
	v_exp_f32_e32 v12, v12
	s_nop 0
	v_add_f32_e32 v12, 1.0, v12
	v_rcp_f32_e32 v12, v12
	s_nop 0
	v_mul_f32_e32 v10, v12, v10
	v_mul_f32_e32 v10, v10, v11
	v_cvt_pk_bf16_f32 v10, v10, v157
	ds_write_b16 v54, v10 offset:9536
	v_mov_b32_e32 v10, v187
	s_nop 0
	s_waitcnt lgkmcnt(0)
	v_lshlrev_b32_e32 v10, 16, v10
	v_mul_f32_e32 v11, 0xbfb8aa3b, v10
	v_exp_f32_e32 v11, v11
	s_nop 0
	v_add_f32_e32 v11, 1.0, v11
	v_rcp_f32_e32 v11, v11
	s_nop 0
	v_mul_f32_e32 v10, v11, v10
	v_mul_f32_e32 v7, v10, v7
	v_cvt_pk_bf16_f32 v7, v7, v157
	ds_write_b16 v54, v7 offset:9568
	v_mov_b32_e32 v7, v188
	s_nop 0
	s_waitcnt lgkmcnt(0)
	v_lshlrev_b32_e32 v7, 16, v7
	v_mul_f32_e32 v10, 0xbfb8aa3b, v7
	v_exp_f32_e32 v10, v10
	s_nop 0
	v_add_f32_e32 v10, 1.0, v10
	v_rcp_f32_e32 v10, v10
	s_nop 0
	v_mul_f32_e32 v7, v10, v7
	v_mul_f32_e32 v6, v6, v7
	v_cvt_pk_bf16_f32 v6, v6, v157
	ds_write_b16 v54, v6 offset:9600
	v_pk_add_f32 v[6:7], v[20:21], v[8:9]
	v_mov_b32_e32 v20, v9
	v_add_f32_e32 v6, v6, v7
	s_nop 1
	s_waitcnt lgkmcnt(0)
; #define LAS __attribute__((address_space(3)))
; __device__ __forceinline__ float bf2f(bf16_t b) { return __uint_as_float((unsigned)b << 16); }
; __device__ __forceinline__ bf16_t f2bf(float f) { return (bf16_t)(pk2(f, 0.f) & 0xffffu); }
; __device__ __forceinline__ float silu_acc(float x) { return x * frcp(1.0f + fexp(-x)); }
; #define LBAR() do { asm volatile("s_waitcnt lgkmcnt(0)" ::: "memory"); __builtin_amdgcn_s_barrier(); asm volatile("" ::: "memory"); } while (0)
; __device__ __forceinline__ void mixer_out_phase(const Ctx& X, LAS unsigned char* lds, int layer, int tid, int wave, int lane) {
;     ...
;             for (int j = 0; j < 4; ++j) {
;                 float sm = (acc[0][j] + acc[1][j]) + (acc[2][j] + acc[3][j]);
;                 sm += __shfl_xor(sm, 1); sm += __shfl_xor(sm, 2); sm += __shfl_xor(sm, 4); sm += __shfl_xor(sm, 8);
;                 const float mu = mixer == 0 ? sm * (1.f / 64.f) : 0.f;
;                 float d[4], s2 = 0.f;
; #pragma unroll
;                 for (int ct = 0; ct < 4; ++ct) { d[ct] = acc[ct][j] - mu; s2 += d[ct] * d[ct]; }
;                 s2 += __shfl_xor(s2, 1); s2 += __shfl_xor(s2, 2); s2 += __shfl_xor(s2, 4); s2 += __shfl_xor(s2, 8);
;                 const float rs = rsqrtf(s2 * (1.f / 64.f) + (mixer == 0 ? 1e-5f : 1e-6f));
;                 const int ii = 16 * (2 * half + rt) + 4 * q + j;
; #pragma unroll
;                 for (int ct = 0; ct < 4; ++ct) { LAS bf16_t* gp = GT + ii * GP + h * 64 + 16 * ct + r;
;                     const float y = d[ct] * rs * wv[ct] * silu_acc(bf2f(*gp));
;                     *gp = on ? f2bf(y) : (bf16_t)0; }
;             }
;         }
;         LBAR();
; #pragma unroll
;         for (int n = 0; n < 4; ++n) { const int idx = tid + 512 * n; __builtin_nontemporal_store(*(const LAS u32x4*)(GT + (idx >> 5) * GP + (idx & 31) * 8), (u32x4*)(mix + (row0 + (idx >> 5)) * D + moff + (idx & 31) * 8)); }
;         LBAR();
	v_add_f32_dpp v6, v6, v6 quad_perm:[1,0,3,2] row_mask:0xf bank_mask:0xf
	s_nop 1
	s_waitcnt lgkmcnt(0)
	v_add_f32_dpp v6, v6, v6 quad_perm:[2,3,0,1] row_mask:0xf bank_mask:0xf
	s_nop 1
	s_waitcnt lgkmcnt(0)
	v_add_f32_dpp v6, v6, v6 row_half_mirror row_mask:0xf bank_mask:0xf
	s_nop 1
	s_waitcnt lgkmcnt(0)
	v_add_f32_dpp v6, v6, v6 row_mirror row_mask:0xf bank_mask:0xf
	v_mul_f32_e32 v6, 0x3c800000, v6
	v_cndmask_b32_e32 v6, 0, v6, vcc
	v_pk_add_f32 v[10:11], v[24:25], v[6:7] op_sel_hi:[1,0] neg_lo:[0,1] neg_hi:[0,1]
	v_pk_add_f32 v[6:7], v[20:21], v[6:7] op_sel_hi:[1,0] neg_lo:[0,1] neg_hi:[0,1]
	v_pk_mul_f32 v[12:13], v[10:11], v[10:11]
	v_pk_mul_f32 v[8:9], v[6:7], v[6:7]
	v_add_f32_e32 v12, v12, v13
	v_add_f32_e32 v9, v9, v12
	v_add_f32_e32 v8, v8, v9
	s_nop 1
	s_waitcnt lgkmcnt(0)
	v_add_f32_dpp v8, v8, v8 quad_perm:[1,0,3,2] row_mask:0xf bank_mask:0xf
	s_nop 1
	s_waitcnt lgkmcnt(0)
	v_add_f32_dpp v8, v8, v8 quad_perm:[2,3,0,1] row_mask:0xf bank_mask:0xf
	s_nop 1
	s_waitcnt lgkmcnt(0)
	v_add_f32_dpp v8, v8, v8 row_half_mirror row_mask:0xf bank_mask:0xf
	s_nop 1
	s_waitcnt lgkmcnt(0)
	v_add_f32_dpp v8, v8, v8 row_mirror row_mask:0xf bank_mask:0xf
	v_fmac_f32_e32 v107, 0x3c800000, v8
	v_cmp_gt_f32_e32 vcc, s3, v107
	v_mul_f32_e32 v8, 0x4b800000, v107
	s_nop 0
	v_cndmask_b32_e32 v8, v107, v8, vcc
	v_rsq_f32_e32 v8, v8
	s_nop 0
	v_mul_f32_e32 v9, 0x45800000, v8
	v_cndmask_b32_e32 v8, v8, v9, vcc
	v_mov_b32_e32 v9, v189
	s_nop 0
	v_mul_f32_e32 v10, v10, v8
	v_mul_f32_e32 v10, v106, v10
	v_mul_f32_e32 v7, v7, v8
	v_mul_f32_e32 v7, v101, v7
	s_waitcnt lgkmcnt(0)
	v_lshlrev_b32_e32 v9, 16, v9
	v_mul_f32_e32 v12, 0xbfb8aa3b, v9
	v_exp_f32_e32 v12, v12
	v_mul_f32_e32 v6, v6, v8
	v_mul_f32_e32 v6, v99, v6
	v_add_f32_e32 v12, 1.0, v12
	v_rcp_f32_e32 v12, v12
	s_nop 0
	v_mul_f32_e32 v9, v12, v9
	v_mul_f32_e32 v9, v9, v10
	v_cvt_pk_bf16_f32 v9, v9, v157
	ds_write_b16 v54, v9 offset:10032
	v_mov_b32_e32 v9, v190
	s_nop 0
	v_lshlrev_b64 v[12:13], 11, v[92:93]
	s_waitcnt lgkmcnt(0)
	v_lshlrev_b32_e32 v9, 16, v9
	v_mul_f32_e32 v10, 0xbfb8aa3b, v9
	v_exp_f32_e32 v10, v10
	s_nop 0
	v_add_f32_e32 v10, 1.0, v10
	v_rcp_f32_e32 v10, v10
	s_nop 0
	v_mul_f32_e32 v9, v10, v9
	v_mul_f32_e32 v10, v11, v8
	v_mul_f32_e32 v10, v103, v10
	v_mul_f32_e32 v9, v9, v10
	v_cvt_pk_bf16_f32 v9, v9, v157
	ds_write_b16 v54, v9 offset:10064
	v_mov_b32_e32 v9, v191
	s_nop 0
	s_waitcnt lgkmcnt(0)
	v_lshlrev_b32_e32 v9, 16, v9
	v_mul_f32_e32 v10, 0xbfb8aa3b, v9
	v_exp_f32_e32 v10, v10
	s_nop 0
	v_add_f32_e32 v10, 1.0, v10
	v_rcp_f32_e32 v10, v10
	s_nop 0
	v_mul_f32_e32 v9, v10, v9
	v_mul_f32_e32 v7, v9, v7
	v_cvt_pk_bf16_f32 v7, v7, v157
	ds_write_b16 v54, v7 offset:10096
	v_mov_b32_e32 v7, v192
	s_nop 0
	v_lshl_add_u64 v[10:11], s[0:1], 0, v[156:157]
	v_lshl_add_u64 v[12:13], v[10:11], 0, v[12:13]
	s_waitcnt lgkmcnt(0)
	v_lshlrev_b32_e32 v7, 16, v7
	v_mul_f32_e32 v9, 0xbfb8aa3b, v7
	v_exp_f32_e32 v9, v9
	s_nop 0
	v_add_f32_e32 v9, 1.0, v9
	v_rcp_f32_e32 v9, v9
	s_nop 0
	v_mul_f32_e32 v7, v9, v7
	v_mul_f32_e32 v6, v6, v7
	v_cvt_pk_bf16_f32 v6, v6, v157
	ds_write_b16 v54, v6 offset:10128
	s_waitcnt lgkmcnt(0)
	s_barrier
	ds_read_b128 v[6:9], v96
	s_waitcnt lgkmcnt(0)
	global_store_dwordx4 v[12:13], v[6:9], off nt
	ds_read_b128 v[6:9], v94
	v_lshlrev_b64 v[12:13], 11, v[90:91]
	v_lshl_add_u64 v[12:13], v[10:11], 0, v[12:13]
	s_waitcnt lgkmcnt(0)
	global_store_dwordx4 v[12:13], v[6:9], off nt
	ds_read_b128 v[6:9], v76
	v_lshlrev_b64 v[12:13], 11, v[88:89]
	v_lshl_add_u64 v[12:13], v[10:11], 0, v[12:13]
	s_waitcnt lgkmcnt(0)
	global_store_dwordx4 v[12:13], v[6:9], off nt
	ds_read_b128 v[6:9], v74
	v_lshlrev_b64 v[12:13], 11, v[86:87]
	v_lshl_add_u64 v[10:11], v[10:11], 0, v[12:13]
	s_waitcnt lgkmcnt(0)
	global_store_dwordx4 v[10:11], v[6:9], off nt
	s_waitcnt lgkmcnt(0)
	s_barrier
	s_cbranch_scc1 .LBB0_888
	v_readlane_b32 s54, v255, 7
	v_readlane_b32 s56, v255, 9
	v_readlane_b32 s58, v255, 11
	v_readlane_b32 s48, v255, 13
	v_readlane_b32 s50, v255, 15
	v_readlane_b32 s52, v255, 17
	v_readlane_b32 s55, v255, 8
	v_readlane_b32 s57, v255, 10
	v_readlane_b32 s59, v255, 12
	v_readlane_b32 s49, v255, 14
	v_readlane_b32 s51, v255, 16
	v_readlane_b32 s53, v255, 18
	s_mov_b64 s[22:23], s[64:65]
	v_readlane_b32 s19, v255, 26

; #define PG8_STAGE(bufoff, gbase, voff) do { _Pragma("unroll") for (int _i = 0; _i < 2; ++_i) \
;         __builtin_amdgcn_global_load_lds((const unsigned*)((const char*)(gbase) + (voff)[_i]), (PG8_LAS unsigned*)(lds + (bufoff) + ldsw + _i * 8192), 16, 0, 0); } while (0)
; #define PG8_BAR __builtin_amdgcn_s_barrier()
; template <class Epi, class Sched, bool ALIGN_EPI = false, bool SP2 = false>
; __device__ __forceinline__ void gemm_phase(PG8_LAS unsigned char* lds, const Gemm g, const Sched& S, const Epi& E) {
;     ...
;     for (int i = 0; i < 2; ++i) { int R, C; stage_rc(tid * 16 + i * 8192, R, C); const int Rb = Epi::PERM ? ((R & ~31) + perm32(R & 31)) : R;
;         voffA[i] = (unsigned)(R * K + C) * 2u; voffB[i] = (unsigned)(Rb * K + C) * 2u; }
;     const size_t kstep = (size_t)(BK * 2);
;     const size_t hstep = (size_t)HALF * K * 2;
;     const size_t tstep = 2 * hstep;
;     const unsigned ldsw = (unsigned)wid * 1024u;
;     const int aoff = lds_byte(wr * 64 + fr, fq * 8), boff = lds_byte(wc * 32 + fr, fq * 8);
;     ...
;     Unit cur, nxt; int ui = 0;
;     float rsv[8];
;     if (!S.next(0, cur)) return;
;     f32x4 acc[2][2][4][2];
; #pragma unroll
;     for (int a = 0; a < 2; ++a)
; #pragma unroll
;         for (int b = 0; b < 2; ++b)
; #pragma unroll
;             for (int m = 0; m < 4; ++m)
; #pragma unroll
;                 for (int n = 0; n < 2; ++n) acc[a][b][m][n] = (f32x4){0.f, 0.f, 0.f, 0.f};
;     bf16x8 At[4][2], B0[2][2], B1[2][2];
;     const char* cA = (const char*)g.A + (size_t)cur.pm * tstep; const char* cB = (const char*)g.Bt + (size_t)cur.pn * tstep;
;     S.a_ready(cur);
;     if constexpr (SP2) {
;         PG8_STAGE(PG8_SB(0, 0), cB, voffB); PG8_STAGE(PG8_SB(0, 1), cB + hstep, voffB); PG8_STAGE(PG8_SA(0, 0), cA, voffA); PG8_STAGE(PG8_SA(0, 1), cA + hstep, voffA);
;         if (wr == 1) PG8_BAR;
.Lgs3_done:
	s_waitcnt vmcnt(0)
	s_branch .Lgs3_pad
	s_nop 0
	s_nop 0
	s_nop 0
	s_nop 0
	s_nop 0
	s_nop 0
	s_nop 0
	s_nop 0
	s_nop 0
	s_nop 0
	s_nop 0
	s_nop 0
	s_nop 0
	s_nop 0
	s_nop 0
	s_nop 0
	s_nop 0
	s_nop 0
	s_nop 0
	s_nop 0
	s_nop 0
	s_nop 0
	s_nop 0
	s_nop 0
	s_nop 0
	s_nop 0
	s_nop 0
	s_nop 0
	s_nop 0
	s_nop 0
	s_nop 0
	s_nop 0
	s_nop 0
	s_nop 0
	s_nop 0
	s_nop 0
	s_nop 0
	s_nop 0
	s_nop 0
	s_nop 0
	s_nop 0
	s_nop 0
	s_nop 0
	s_nop 0
	s_nop 0
	s_nop 0
	s_nop 0
	s_nop 0
	s_nop 0
	s_nop 0
	s_nop 0
	s_nop 0
	s_nop 0
	s_nop 0
	s_nop 0
	s_nop 0
	s_nop 0
	s_nop 0
	s_nop 0
	s_nop 0
	s_nop 0
	s_nop 0
.Lgs3_pad:
.LBB0_942:
	s_or_b64 exec, exec, s[0:1]
	s_and_b64 s[0:1], s[26:27], exec
	v_readlane_b32 s0, v253, 63
	v_readlane_b32 s1, v254, 0
	s_waitcnt vmcnt(0)
	v_mov_b32_e32 v10, v224
	s_waitcnt lgkmcnt(0)
	v_cndmask_b32_e64 v6, 0, 1, s[0:1]
	v_cmp_ne_u32_e64 s[4:5], 1, v6
	s_barrier
	s_nop 0
	v_writelane_b32 v255, s4, 32
	s_cselect_b32 s35, 0, s29
	s_cselect_b32 s34, 0, s28
	v_writelane_b32 v255, s5, 33
	s_andn2_b64 vcc, exec, s[0:1]
	v_readfirstlane_b32 s6, v10
	s_cbranch_vccnz .LBB0_1042
	v_lshlrev_b32_e32 v6, 4, v10
	v_add_u32_e32 v7, 0x2000, v6
	v_ashrrev_i32_e32 v8, 31, v7
	v_lshrrev_b32_e32 v8, 22, v8
	v_add_u32_e32 v8, v7, v8
	v_ashrrev_i32_e32 v11, 10, v8
	v_mul_i32_i24_e32 v8, 0x400, v11
	v_sub_u32_e32 v7, v7, v8
	v_lshrrev_b32_e32 v8, 4, v7
	v_bitop3_b32 v7, v8, v7, 32 bitop3:0x6c
	v_ashrrev_i32_e32 v8, 31, v7
	v_readlane_b32 s0, v254, 61
	v_lshrrev_b32_e32 v8, 26, v8
	v_readlane_b32 s1, v254, 62
	v_add_u32_e32 v8, v7, v8
	v_lshlrev_b32_e32 v9, 3, v11
	s_lshl_b64 s[0:1], s[0:1], 21
	v_readlane_b32 s4, v253, 54
	v_ashrrev_i32_e32 v12, 6, v8
	v_and_b32_e32 v9, -16, v9
	s_add_u32 s16, s4, s0
	v_readlane_b32 s0, v253, 55
	v_add_u32_e32 v9, v12, v9
	s_addc_u32 s19, s0, s1
	v_and_b32_e32 v13, 3, v12
	s_mov_b32 s0, 0x1fffe0
	v_lshrrev_b32_e32 v14, 2, v9
	v_lshlrev_b32_e32 v15, 1, v9
	v_and_b32_e32 v8, 0xc0, v8
	v_and_or_b32 v13, v9, s0, v13
	v_and_b32_e32 v14, 4, v14
	v_and_b32_e32 v15, 24, v15
	v_sub_u32_e32 v7, v7, v8
	v_or3_b32 v14, v13, v14, v15
	v_lshlrev_b32_e32 v13, 5, v11
	v_ashrrev_i16_sdwa v7, v228, sext(v7) dst_sel:DWORD dst_unused:UNUSED_PAD src0_sel:DWORD src1_sel:BYTE_0
	v_and_b32_e32 v15, 32, v13
	v_bfe_i32 v13, v7, 0, 16
	v_add_lshl_u32 v7, v15, v13, 1
	v_lshl_add_u32 v142, v14, 11, v7
	v_lshl_add_u32 v144, v9, 11, v7
	v_bfe_i32 v7, v10, 27, 1
	v_lshrrev_b32_e32 v7, 22, v7
	v_add_u32_e32 v7, v6, v7
	v_and_b32_e32 v7, 0xfffffc00, v7
	v_sub_u32_e32 v6, v6, v7
	v_lshrrev_b32_e32 v7, 4, v6
	v_ashrrev_i32_e32 v8, 31, v10
	v_bitop3_b32 v6, v7, v6, 32 bitop3:0x6c
	v_lshrrev_b32_e32 v8, 26, v8
	v_ashrrev_i32_e32 v7, 31, v6
	v_add_u32_e32 v8, v10, v8
	v_lshrrev_b32_e32 v7, 26, v7
	v_ashrrev_i32_e32 v15, 6, v8
	v_add_u32_e32 v7, v6, v7
	v_lshlrev_b32_e32 v8, 3, v15
	v_ashrrev_i32_e32 v14, 6, v7
	v_and_b32_e32 v8, -16, v8
	v_add_u32_e32 v8, v14, v8
	v_and_b32_e32 v9, 3, v14
	v_lshrrev_b32_e32 v16, 2, v8
	v_lshlrev_b32_e32 v17, 1, v8
	v_and_b32_e32 v7, 0xc0, v7
	s_ashr_i32 s8, s6, 6
	v_and_or_b32 v9, v8, s0, v9
	v_and_b32_e32 v16, 4, v16
	v_and_b32_e32 v17, 24, v17
	v_sub_u32_e32 v6, v6, v7
	s_ashr_i32 s7, s6, 8
	s_lshl_b32 s33, s8, 10
	v_or3_b32 v9, v9, v16, v17
	v_lshlrev_b32_e32 v16, 5, v15
	v_ashrrev_i16_sdwa v6, v228, sext(v6) dst_sel:DWORD dst_unused:UNUSED_PAD src0_sel:DWORD src1_sel:BYTE_0
	v_readlane_b32 s0, v254, 26
	v_and_b32_e32 v17, 32, v16
	v_bfe_i32 v16, v6, 0, 16
	v_readlane_b32 s1, v254, 27
	s_add_u32 s4, s16, s0
	v_add_lshl_u32 v6, v17, v16, 1
	s_addc_u32 s5, s19, s1
	s_add_i32 s80, s33, 0
	v_lshl_add_u32 v156, v9, 11, v6
	s_add_i32 m0, s80, 0x10000
	v_lshl_add_u32 v146, v8, 11, v6
	global_load_lds_dwordx4 v156, s[4:5]
	s_add_i32 m0, s80, 0x12000
	s_add_u32 s0, s4, 0x40000
	global_load_lds_dwordx4 v142, s[4:5]
	s_addc_u32 s1, s5, 0
	s_add_i32 m0, s80, 0x14000
	s_add_i32 s81, s80, 0x2000
	global_load_lds_dwordx4 v156, s[0:1]
	s_add_i32 m0, s80, 0x16000
	s_add_i32 s87, s80, 0x4000
	global_load_lds_dwordx4 v142, s[0:1]
	v_readlane_b32 s0, v254, 28
	s_mov_b32 m0, s80
	v_readlane_b32 s1, v254, 29
	s_add_i32 s88, s80, 0x6000
	v_mov_b32_e32 v143, v157
	s_cmp_eq_u32 s7, 1
	v_lshl_add_u64 v[6:7], s[4:5], 0, v[156:157]
	v_lshl_add_u64 v[8:9], s[4:5], 0, v[142:143]
	global_load_lds_dwordx4 v146, s[0:1]
	s_mov_b32 m0, s81
	s_nop 0
	global_load_lds_dwordx4 v144, s[0:1]
	v_readlane_b32 s0, v254, 30
	s_mov_b32 m0, s87
	v_readlane_b32 s1, v254, 31
	s_nop 4
	global_load_lds_dwordx4 v146, s[0:1]
	s_mov_b32 m0, s88
	s_nop 0
	global_load_lds_dwordx4 v144, s[0:1]
	s_cselect_b64 s[0:1], -1, 0
	s_cmp_lg_u32 s7, 1
	s_cbranch_scc1 .LBB0_945
	s_barrier
